# attention tile loops: 8-wave ping-pong (halves offset by half a tile, 2 barriers per tile, prio raise in MFMA segment), tile DMA at softmax head with K 2 tiles / V 1 tile ahead
# speedup vs baseline: 1.0143x; 1.0095x over previous
.LBB0_713:
	s_mov_b32 m0, s31
	s_xor_b64 s[14:15], s[16:17], -1
	s_and_b64 s[16:17], s[16:17], exec
	s_barrier
	global_load_lds_dwordx4 v[174:175], off
	s_mov_b32 m0, s37
	s_cselect_b32 s6, s44, s43
	global_load_lds_dwordx4 v[176:177], off
	s_add_i32 m0, s41, 0x4000
	s_lshr_b32 s52, s6, 6
	global_load_lds_dwordx4 v[178:179], off
	s_add_i32 m0, s31, 0x6000
	v_mov_b32_e32 v2, v194
	global_load_lds_dwordx4 v[180:181], off
	s_add_i32 m0, s31, 0x6400
	v_mov_b32_e32 v14, v0
	global_load_lds_dwordx4 v[182:183], off
	s_mov_b32 m0, s35
	v_mov_b32_e32 v15, v0
	global_load_lds_dwordx4 v[184:185], off
	s_mov_b32 m0, s38
	s_waitcnt lgkmcnt(0)
	v_mov_b32_e32 v1, v0
	global_load_lds_dwordx4 v[186:187], off
	s_add_i32 m0, s41, 0xe000
	v_mov_b32_e32 v4, v0
	global_load_lds_dwordx4 v[188:189], off
	s_add_i32 m0, s35, 0x6000
	v_mov_b32_e32 v5, v0
	global_load_lds_dwordx4 v[190:191], off
	s_add_i32 m0, s35, 0x6400
	s_add_u32 s16, s48, s6
	s_addc_u32 s17, s49, 0
	s_mul_i32 s18, s17, 0x1800
	s_mul_hi_u32 s19, s16, 0x1800
	s_add_i32 s19, s19, s18
	s_mul_i32 s18, s16, 0x1800
	s_add_u32 s18, s50, s18
	global_load_lds_dwordx4 v[192:193], off
	s_addc_u32 s19, s51, s19
	v_ashrrev_i32_e32 v3, 31, v2
	v_lshl_add_u64 v[2:3], v[2:3], 1, s[18:19]
	global_load_dwordx4 v[112:115], v[2:3], off
	global_load_dwordx4 v[116:119], v[2:3], off offset:32
	global_load_dwordx4 v[120:123], v[2:3], off offset:64
	global_load_dwordx4 v[124:127], v[2:3], off offset:96
	global_load_dwordx4 v[128:131], v[2:3], off offset:128
	global_load_dwordx4 v[132:135], v[2:3], off offset:160
	global_load_dwordx4 v[136:139], v[2:3], off offset:192
	global_load_dwordx4 v[140:143], v[2:3], off offset:224
	global_load_dwordx4 v[144:147], v[2:3], off offset:256
	global_load_dwordx4 v[148:151], v[2:3], off offset:288
	global_load_dwordx4 v[152:155], v[2:3], off offset:320
	global_load_dwordx4 v[156:159], v[2:3], off offset:352
	s_add_i32 s6, s6, s36
	s_waitcnt vmcnt(0)
	v_mov_b32_e32 v2, v0
	v_mov_b32_e32 v3, v0
	v_mov_b32_e32 v6, v0
	v_mov_b32_e32 v7, v0
	v_mov_b32_e32 v8, v0
	v_mov_b32_e32 v9, v0
	v_mov_b32_e32 v10, v0
	v_mov_b32_e32 v11, v0
	v_mov_b32_e32 v12, v0
	v_mov_b32_e32 v13, v0
	s_or_b32 s59, s6, 63
	v_mov_b64_e32 v[62:63], v[14:15]
	v_mov_b64_e32 v[78:79], v[14:15]
	v_mov_b64_e32 v[94:95], v[14:15]
	v_mov_b64_e32 v[110:111], v[14:15]
	s_mov_b32 s53, 63
	s_mov_b32 s54, 0
	s_add_i32 s55, s52, 4
	s_or_b32 s58, s52, 3
	v_add_u32_e32 v216, s59, v213
	v_mov_b32_e32 v218, 0
	v_mov_b32_e32 v217, 0xf149f2ca
	s_mov_b32 s61, 2
	s_mov_b32 s60, -4
	v_mov_b64_e32 v[60:61], v[12:13]
	v_mov_b64_e32 v[58:59], v[10:11]
	v_mov_b64_e32 v[56:57], v[8:9]
	v_mov_b64_e32 v[54:55], v[6:7]
	v_mov_b64_e32 v[52:53], v[4:5]
	s_waitcnt vmcnt(0)
	s_waitcnt lgkmcnt(0)
	s_barrier
	v_mov_b64_e32 v[50:51], v[2:3]
	v_mov_b64_e32 v[48:49], v[0:1]
	v_mov_b64_e32 v[76:77], v[12:13]
	v_mov_b64_e32 v[74:75], v[10:11]
	v_mov_b64_e32 v[72:73], v[8:9]
	v_mov_b64_e32 v[70:71], v[6:7]
	v_mov_b64_e32 v[68:69], v[4:5]
	v_mov_b64_e32 v[66:67], v[2:3]
	v_mov_b64_e32 v[64:65], v[0:1]
	v_mov_b64_e32 v[92:93], v[12:13]
	v_mov_b64_e32 v[90:91], v[10:11]
	v_mov_b64_e32 v[88:89], v[8:9]
	v_mov_b64_e32 v[86:87], v[6:7]
	v_mov_b64_e32 v[84:85], v[4:5]
	v_mov_b64_e32 v[82:83], v[2:3]
	v_mov_b64_e32 v[80:81], v[0:1]
	v_mov_b64_e32 v[108:109], v[12:13]
	v_mov_b64_e32 v[106:107], v[10:11]
	v_mov_b64_e32 v[104:105], v[8:9]
	v_mov_b64_e32 v[102:103], v[6:7]
	v_mov_b64_e32 v[100:101], v[4:5]
	v_mov_b64_e32 v[98:99], v[2:3]
	v_mov_b64_e32 v[96:97], v[0:1]
	s_cmp_lt_u32 s33, 4
	s_cbranch_scc1 .LPP0_pre
	s_barrier
.LPP0_pre:
	s_branch .LBB0_717

.LBB0_715:
	v_add_f32_e32 v14, v14, v15
	v_fmac_f32_e32 v14, v218, v1
	s_cmp_lt_u32 s33, 4
	s_cbranch_scc0 .LPP0_b2
	s_waitcnt vmcnt(5)
.LPP0_b2:
	s_waitcnt lgkmcnt(0)
	s_barrier
	s_setprio 1
	v_add_u32_e32 v1, s62, v212
	ds_read_b64_tr_b16 v[218:219], v1 offset:0
	ds_read_b64_tr_b16 v[220:221], v1 offset:0x800
	ds_read_b64_tr_b16 v[222:223], v1 offset:0x200
	ds_read_b64_tr_b16 v[224:225], v1 offset:0xa00
	ds_read_b64_tr_b16 v[226:227], v1 offset:0x400
	ds_read_b64_tr_b16 v[228:229], v1 offset:0xc00
	ds_read_b64_tr_b16 v[230:231], v1 offset:0x600
	ds_read_b64_tr_b16 v[232:233], v1 offset:0xe00
	ds_read_b64_tr_b16 v[234:235], v1 offset:0x1000
	ds_read_b64_tr_b16 v[236:237], v1 offset:0x1800
	ds_read_b64_tr_b16 v[238:239], v1 offset:0x1200
	ds_read_b64_tr_b16 v[240:241], v1 offset:0x1a00
	ds_read_b64_tr_b16 v[242:243], v1 offset:0x1400
	ds_read_b64_tr_b16 v[244:245], v1 offset:0x1c00
	ds_read_b64_tr_b16 v[246:247], v1 offset:0x1600
	ds_read_b64_tr_b16 v[248:249], v1 offset:0x1e00
	s_waitcnt lgkmcnt(8)
	s_nop 0
	v_mfma_f32_32x32x16_bf16 v[96:111], v[160:163], v[218:221], v[96:111]
	v_mfma_f32_32x32x16_bf16 v[80:95], v[160:163], v[222:225], v[80:95]
	v_mfma_f32_32x32x16_bf16 v[64:79], v[160:163], v[226:229], v[64:79]
	v_mfma_f32_32x32x16_bf16 v[48:63], v[160:163], v[230:233], v[48:63]
	ds_read_b64_tr_b16 v[160:161], v1 offset:0x2000
	ds_read_b64_tr_b16 v[162:163], v1 offset:0x2800
	ds_read_b64_tr_b16 v[218:219], v1 offset:0x2200
	ds_read_b64_tr_b16 v[220:221], v1 offset:0x2a00
	ds_read_b64_tr_b16 v[222:223], v1 offset:0x2400
	ds_read_b64_tr_b16 v[224:225], v1 offset:0x2c00
	ds_read_b64_tr_b16 v[226:227], v1 offset:0x2600
	ds_read_b64_tr_b16 v[228:229], v1 offset:0x2e00
	s_waitcnt lgkmcnt(8)
	v_mfma_f32_32x32x16_bf16 v[96:111], v[10:13], v[234:237], v[96:111]
	v_mfma_f32_32x32x16_bf16 v[80:95], v[10:13], v[238:241], v[80:95]
	v_mfma_f32_32x32x16_bf16 v[64:79], v[10:13], v[242:245], v[64:79]
	v_mfma_f32_32x32x16_bf16 v[48:63], v[10:13], v[246:249], v[48:63]
	ds_read_b64_tr_b16 v[10:11], v1 offset:0x3000
	ds_read_b64_tr_b16 v[12:13], v1 offset:0x3800
	ds_read_b64_tr_b16 v[230:231], v1 offset:0x3200
	ds_read_b64_tr_b16 v[232:233], v1 offset:0x3a00
	ds_read_b64_tr_b16 v[234:235], v1 offset:0x3400
	ds_read_b64_tr_b16 v[236:237], v1 offset:0x3c00
	ds_read_b64_tr_b16 v[238:239], v1 offset:0x3600
	ds_read_b64_tr_b16 v[240:241], v1 offset:0x3e00
	s_waitcnt lgkmcnt(8)
	v_mfma_f32_32x32x16_bf16 v[96:111], v[6:9], v[160:163], v[96:111]
	v_mfma_f32_32x32x16_bf16 v[80:95], v[6:9], v[218:221], v[80:95]
	v_mfma_f32_32x32x16_bf16 v[64:79], v[6:9], v[222:225], v[64:79]
	v_mfma_f32_32x32x16_bf16 v[48:63], v[6:9], v[226:229], v[48:63]
	s_waitcnt lgkmcnt(0)
	v_mfma_f32_32x32x16_bf16 v[96:111], v[2:5], v[10:13], v[96:111]
	v_mfma_f32_32x32x16_bf16 v[80:95], v[2:5], v[230:233], v[80:95]
	v_mfma_f32_32x32x16_bf16 v[64:79], v[2:5], v[234:237], v[64:79]
	v_mfma_f32_32x32x16_bf16 v[48:63], v[2:5], v[238:241], v[48:63]
	v_mov_b32_e32 v218, v14
.LBB0_716:
	s_add_i32 s6, s54, 1
	s_cmp_lg_u32 s54, 2
	s_cselect_b32 s54, s6, 0
	s_add_i32 s6, s61, 1
	s_cmp_lg_u32 s61, 2
	s_cselect_b32 s61, s6, 0
	s_add_i32 s60, s60, 1
	s_add_i32 s53, s53, 64
	s_cmp_eq_u32 s52, s60
	v_subrev_u32_e32 v216, 64, v216
	s_cbranch_scc1 .LBB0_725

.LBB0_719:
	s_setprio 0
	s_cmp_lt_u32 s33, 4
	s_cbranch_scc1 .LPP0_b1
	s_waitcnt vmcnt(0)
.LPP0_b1:
	s_waitcnt lgkmcnt(0)
	s_barrier
	s_add_i32 s6, s60, 6
	s_cmp_lt_u32 s6, s55
	s_cselect_b32 s6, s6, s58
	s_mul_i32 s63, s61, 0xa000
	s_lshl_b32 s6, s6, 6
	s_add_i32 s75, s63, s30
	s_lshl_b64 s[64:65], s[6:7], 12
	s_add_u32 s66, s10, s64
	s_addc_u32 s67, s11, s65
	v_lshl_add_u64 v[2:3], s[66:67], 0, v[172:173]
	s_mov_b32 m0, s75
	s_nop 0
	global_load_lds_dwordx4 v[2:3], off
	v_lshl_add_u64 v[2:3], s[66:67], 0, v[170:171]
	s_add_i32 m0, s75, 0x400
	s_lshl_b64 s[66:67], s[6:7], 7
	s_add_i32 s6, s63, s34
	global_load_lds_dwordx4 v[2:3], off
	v_lshl_add_u64 v[2:3], v[178:179], 0, s[66:67]
	s_add_i32 m0, s6, 0x4000
	s_nop 0
	global_load_lds_dwordx4 v[2:3], off
	s_add_i32 s6, s60, 5
	s_cmp_lt_u32 s6, s55
	s_cselect_b32 s6, s6, s58
	s_lshl_b32 s6, s6, 6
	s_lshl_b64 s[64:65], s[6:7], 12
	s_add_u32 s64, s12, s64
	s_addc_u32 s65, s13, s65
	s_add_i32 s63, s54, 1
	s_cmp_lg_u32 s54, 2
	s_cselect_b32 s63, s63, 0
	s_mul_i32 s63, s63, 0xa000
	s_add_i32 s75, s63, s30
	v_lshl_add_u64 v[2:3], s[64:65], 0, v[168:169]
	s_add_i32 m0, s75, 0x6000
	s_nop 0
	global_load_lds_dwordx4 v[2:3], off
	v_lshl_add_u64 v[2:3], s[64:65], 0, v[166:167]
	s_add_i32 m0, s75, 0x6400
	s_nop 0
	global_load_lds_dwordx4 v[2:3], off
	s_cmp_le_u32 s53, s59
	s_cbranch_scc1 .LBB0_722
	v_cmp_gt_u32_e32 vcc, 2.0, v216
	v_add_u32_e32 v1, 0xbfffffe0, v216
	s_nop 0
	v_cndmask_b32_e32 v16, v215, v16, vcc
	v_cmp_lt_u32_e32 vcc, s39, v1
	v_add_u32_e32 v1, 0xbfffffff, v216
	s_nop 0
	v_cndmask_b32_e32 v32, v215, v32, vcc
	v_cmp_lt_u32_e32 vcc, s39, v1
	v_add_u32_e32 v1, 0xbfffffdf, v216
	s_nop 0
	v_cndmask_b32_e32 v17, v215, v17, vcc
	v_cmp_lt_u32_e32 vcc, s39, v1
	v_add_u32_e32 v1, 0xbffffffe, v216
	s_nop 0
	v_cndmask_b32_e32 v33, v215, v33, vcc
	v_cmp_lt_u32_e32 vcc, s39, v1
	v_add_u32_e32 v1, 0xbfffffde, v216
	s_nop 0
	v_cndmask_b32_e32 v18, v215, v18, vcc
	v_cmp_lt_u32_e32 vcc, s39, v1
	v_add_u32_e32 v1, 0xbffffffd, v216
	s_nop 0
	v_cndmask_b32_e32 v34, v215, v34, vcc
	v_cmp_lt_u32_e32 vcc, s39, v1
	v_add_u32_e32 v1, 0xbfffffdd, v216
	s_nop 0
	v_cndmask_b32_e32 v19, v215, v19, vcc
	v_cmp_lt_u32_e32 vcc, s39, v1
	v_add_u32_e32 v1, 0xbffffff8, v216
	s_nop 0
	v_cndmask_b32_e32 v35, v215, v35, vcc
	v_cmp_lt_u32_e32 vcc, s39, v1
	v_add_u32_e32 v1, 0xbfffffd8, v216
	s_nop 0
	v_cndmask_b32_e32 v20, v215, v20, vcc
	v_cmp_lt_u32_e32 vcc, s39, v1
	v_add_u32_e32 v1, 0xbffffff7, v216
	s_nop 0
	v_cndmask_b32_e32 v36, v215, v36, vcc
	v_cmp_lt_u32_e32 vcc, s39, v1
	v_add_u32_e32 v1, 0xbfffffd7, v216
	s_nop 0
	v_cndmask_b32_e32 v21, v215, v21, vcc
	v_cmp_lt_u32_e32 vcc, s39, v1
	v_add_u32_e32 v1, 0xbffffff6, v216
	s_nop 0
	v_cndmask_b32_e32 v37, v215, v37, vcc
	v_cmp_lt_u32_e32 vcc, s39, v1
	v_add_u32_e32 v1, 0xbfffffd6, v216
	s_nop 0
	v_cndmask_b32_e32 v22, v215, v22, vcc
	v_cmp_lt_u32_e32 vcc, s39, v1
	v_add_u32_e32 v1, 0xbffffff5, v216
	s_nop 0
	v_cndmask_b32_e32 v38, v215, v38, vcc
	v_cmp_lt_u32_e32 vcc, s39, v1
	v_add_u32_e32 v1, 0xbfffffd5, v216
	s_nop 0
	v_cndmask_b32_e32 v23, v215, v23, vcc
	v_cmp_lt_u32_e32 vcc, s39, v1
	v_add_u32_e32 v1, 0xbffffff0, v216
	s_nop 0
	v_cndmask_b32_e32 v39, v215, v39, vcc
	v_cmp_lt_u32_e32 vcc, s39, v1
	v_add_u32_e32 v1, 0xbfffffd0, v216
	s_nop 0
	v_cndmask_b32_e32 v24, v215, v24, vcc
	v_cmp_lt_u32_e32 vcc, s39, v1
	v_add_u32_e32 v1, 0xbfffffef, v216
	s_nop 0
	v_cndmask_b32_e32 v40, v215, v40, vcc
	v_cmp_lt_u32_e32 vcc, s39, v1
	v_add_u32_e32 v1, 0xbfffffcf, v216
	s_nop 0
	v_cndmask_b32_e32 v25, v215, v25, vcc
	v_cmp_lt_u32_e32 vcc, s39, v1
	v_add_u32_e32 v1, 0xbfffffee, v216
	s_nop 0
	v_cndmask_b32_e32 v41, v215, v41, vcc
	v_cmp_lt_u32_e32 vcc, s39, v1
	v_add_u32_e32 v1, 0xbfffffce, v216
	s_nop 0
	v_cndmask_b32_e32 v26, v215, v26, vcc
	v_cmp_lt_u32_e32 vcc, s39, v1
	v_add_u32_e32 v1, 0xbfffffed, v216
	s_nop 0
	v_cndmask_b32_e32 v42, v215, v42, vcc
	v_cmp_lt_u32_e32 vcc, s39, v1
	v_add_u32_e32 v1, 0xbfffffcd, v216
	s_nop 0
	v_cndmask_b32_e32 v27, v215, v27, vcc
	v_cmp_lt_u32_e32 vcc, s39, v1
	v_add_u32_e32 v1, 0xbfffffe8, v216
	s_nop 0
	v_cndmask_b32_e32 v43, v215, v43, vcc
	v_cmp_lt_u32_e32 vcc, s39, v1
	v_add_u32_e32 v1, 0xbfffffc8, v216
	s_nop 0
	v_cndmask_b32_e32 v28, v215, v28, vcc
	v_cmp_lt_u32_e32 vcc, s39, v1
	v_add_u32_e32 v1, 0xbfffffe7, v216
	s_nop 0
	v_cndmask_b32_e32 v44, v215, v44, vcc
	v_cmp_lt_u32_e32 vcc, s39, v1
	v_add_u32_e32 v1, 0xbfffffc7, v216
	s_nop 0
	v_cndmask_b32_e32 v29, v215, v29, vcc
	v_cmp_lt_u32_e32 vcc, s39, v1
	v_add_u32_e32 v1, 0xbfffffe6, v216
	s_nop 0
	v_cndmask_b32_e32 v45, v215, v45, vcc
	v_cmp_lt_u32_e32 vcc, s39, v1
	v_add_u32_e32 v1, 0xbfffffc6, v216
	s_nop 0
	v_cndmask_b32_e32 v30, v215, v30, vcc
	v_cmp_lt_u32_e32 vcc, s39, v1
	v_add_u32_e32 v1, 0xbfffffe5, v216
	s_nop 0
	v_cndmask_b32_e32 v46, v215, v46, vcc
	v_cmp_lt_u32_e32 vcc, s39, v1
	v_add_u32_e32 v1, 0xbfffffc5, v216
	s_nop 0
	v_cndmask_b32_e32 v31, v215, v31, vcc
	v_cmp_lt_u32_e32 vcc, s39, v1
	s_nop 1
	v_cndmask_b32_e32 v47, v215, v47, vcc

.LPP0_noact:
	s_cmp_lt_u32 s33, 4
	s_cbranch_scc1 .LPP0_na1
	s_waitcnt vmcnt(0)
	s_barrier
	s_add_i32 s6, s60, 6
	s_cmp_lt_u32 s6, s55
	s_cselect_b32 s6, s6, s58
	s_mul_i32 s63, s61, 0xa000
	s_lshl_b32 s6, s6, 6
	s_add_i32 s75, s63, s30
	s_lshl_b64 s[64:65], s[6:7], 12
	s_add_u32 s66, s10, s64
	s_addc_u32 s67, s11, s65
	v_lshl_add_u64 v[2:3], s[66:67], 0, v[172:173]
	s_mov_b32 m0, s75
	s_nop 0
	global_load_lds_dwordx4 v[2:3], off
	v_lshl_add_u64 v[2:3], s[66:67], 0, v[170:171]
	s_add_i32 m0, s75, 0x400
	s_lshl_b64 s[66:67], s[6:7], 7
	s_add_i32 s6, s63, s34
	global_load_lds_dwordx4 v[2:3], off
	v_lshl_add_u64 v[2:3], v[178:179], 0, s[66:67]
	s_add_i32 m0, s6, 0x4000
	s_nop 0
	global_load_lds_dwordx4 v[2:3], off
	s_add_i32 s6, s60, 5
	s_cmp_lt_u32 s6, s55
	s_cselect_b32 s6, s6, s58
	s_lshl_b32 s6, s6, 6
	s_lshl_b64 s[64:65], s[6:7], 12
	s_add_u32 s64, s12, s64
	s_addc_u32 s65, s13, s65
	s_add_i32 s63, s54, 1
	s_cmp_lg_u32 s54, 2
	s_cselect_b32 s63, s63, 0
	s_mul_i32 s63, s63, 0xa000
	s_add_i32 s75, s63, s30
	v_lshl_add_u64 v[2:3], s[64:65], 0, v[168:169]
	s_add_i32 m0, s75, 0x6000
	s_nop 0
	global_load_lds_dwordx4 v[2:3], off
	v_lshl_add_u64 v[2:3], s[64:65], 0, v[166:167]
	s_add_i32 m0, s75, 0x6400
	s_nop 0
	global_load_lds_dwordx4 v[2:3], off
	s_barrier
	s_branch .LBB0_716
.LPP0_na1:
	s_barrier
	s_add_i32 s6, s60, 6
	s_cmp_lt_u32 s6, s55
	s_cselect_b32 s6, s6, s58
	s_mul_i32 s63, s61, 0xa000
	s_lshl_b32 s6, s6, 6
	s_add_i32 s75, s63, s30
	s_lshl_b64 s[64:65], s[6:7], 12
	s_add_u32 s66, s10, s64
	s_addc_u32 s67, s11, s65
	v_lshl_add_u64 v[2:3], s[66:67], 0, v[172:173]
	s_mov_b32 m0, s75
	s_nop 0
	global_load_lds_dwordx4 v[2:3], off
	v_lshl_add_u64 v[2:3], s[66:67], 0, v[170:171]
	s_add_i32 m0, s75, 0x400
	s_lshl_b64 s[66:67], s[6:7], 7
	s_add_i32 s6, s63, s34
	global_load_lds_dwordx4 v[2:3], off
	v_lshl_add_u64 v[2:3], v[178:179], 0, s[66:67]
	s_add_i32 m0, s6, 0x4000
	s_nop 0
	global_load_lds_dwordx4 v[2:3], off
	s_add_i32 s6, s60, 5
	s_cmp_lt_u32 s6, s55
	s_cselect_b32 s6, s6, s58
	s_lshl_b32 s6, s6, 6
	s_lshl_b64 s[64:65], s[6:7], 12
	s_add_u32 s64, s12, s64
	s_addc_u32 s65, s13, s65
	s_add_i32 s63, s54, 1
	s_cmp_lg_u32 s54, 2
	s_cselect_b32 s63, s63, 0
	s_mul_i32 s63, s63, 0xa000
	s_add_i32 s75, s63, s30
	v_lshl_add_u64 v[2:3], s[64:65], 0, v[168:169]
	s_add_i32 m0, s75, 0x6000
	s_nop 0
	global_load_lds_dwordx4 v[2:3], off
	v_lshl_add_u64 v[2:3], s[64:65], 0, v[166:167]
	s_add_i32 m0, s75, 0x6400
	s_nop 0
	global_load_lds_dwordx4 v[2:3], off
	s_waitcnt vmcnt(5)
	s_barrier
	s_branch .LBB0_716
.LBB0_725:
	s_setprio 0
	s_cmp_lt_u32 s33, 4
	s_cbranch_scc0 .LPP0_fin
	s_barrier
.LPP0_fin:
	s_barrier
	s_waitcnt vmcnt(0)
	s_and_saveexec_b64 s[18:19], s[0:1]
	ds_write_b32 v209, v218
	s_or_b64 exec, exec, s[18:19]
	v_mbcnt_lo_u32_b32 v1, -1, 0
	v_mbcnt_hi_u32_b32 v1, -1, v1
	s_lshl_b32 s98, s33, 11
	s_mov_b32 s99, 0x5040100
	s_mov_b32 s100, 0x7060302
	s_waitcnt lgkmcnt(0)
	ds_read_b128 v[32:35], v211
	ds_read_b128 v[36:39], v211 offset:32
	ds_read_b128 v[40:43], v211 offset:64
	ds_read_b128 v[44:47], v211 offset:96
	s_lshl_b64 s[16:17], s[16:17], 12
	s_add_u32 s16, s45, s16
	s_addc_u32 s17, s47, s17
	v_lshrrev_b32_e32 v2, 5, v1
	v_and_b32_e32 v3, 31, v1
	v_lshlrev_b32_e32 v2, 10, v2
	v_lshl_add_u32 v2, v3, 2, v2
	v_add_u32_e32 v2, s98, v2
	v_lshrrev_b32_e32 v4, 4, v1
	v_and_b32_e32 v5, 15, v1
	v_lshlrev_b32_e32 v6, 9, v4
	v_lshl_add_u32 v6, v5, 5, v6
	v_add_u32_e32 v6, s98, v6
	v_lshlrev_b32_e32 v7, 13, v4
	v_lshl_add_u32 v7, v5, 4, v7
	v_add_u32_e32 v3, 0xa000, v2
	v_add_u32_e32 v8, 0xa000, v6
	s_waitcnt lgkmcnt(0)
	v_rcp_f32_e32 v16, v32
	v_rcp_f32_e32 v17, v33
	v_rcp_f32_e32 v18, v34
	v_rcp_f32_e32 v19, v35
	v_rcp_f32_e32 v20, v36
	v_rcp_f32_e32 v21, v37
	v_rcp_f32_e32 v22, v38
	v_rcp_f32_e32 v23, v39
	v_rcp_f32_e32 v24, v40
	v_rcp_f32_e32 v25, v41
	v_rcp_f32_e32 v26, v42
	v_rcp_f32_e32 v27, v43
	v_rcp_f32_e32 v28, v44
	v_rcp_f32_e32 v29, v45
	v_rcp_f32_e32 v30, v46
	v_rcp_f32_e32 v31, v47
	s_nop 0
	v_pk_mul_f32 v[96:97], v[96:97], v[16:17]
	v_pk_mul_f32 v[80:81], v[80:81], v[16:17]
	v_pk_mul_f32 v[64:65], v[64:65], v[16:17]
	v_pk_mul_f32 v[48:49], v[48:49], v[16:17]
	v_cvt_pk_bf16_f32 v96, v96, v97
	v_cvt_pk_bf16_f32 v80, v80, v81
	v_cvt_pk_bf16_f32 v64, v64, v65
	v_cvt_pk_bf16_f32 v48, v48, v49
	ds_write_b32 v2, v96
	ds_write_b32 v2, v80 offset:128
	ds_write_b32 v2, v64 offset:256
	ds_write_b32 v2, v48 offset:384
	v_pk_mul_f32 v[98:99], v[98:99], v[18:19]
	v_pk_mul_f32 v[82:83], v[82:83], v[18:19]
	v_pk_mul_f32 v[66:67], v[66:67], v[18:19]
	v_pk_mul_f32 v[50:51], v[50:51], v[18:19]
	v_cvt_pk_bf16_f32 v98, v98, v99
	v_cvt_pk_bf16_f32 v82, v82, v83
	v_cvt_pk_bf16_f32 v66, v66, v67
	v_cvt_pk_bf16_f32 v50, v50, v51
	ds_write_b32 v2, v98 offset:512
	ds_write_b32 v2, v82 offset:640
	ds_write_b32 v2, v66 offset:768
	ds_write_b32 v2, v50 offset:896
	v_pk_mul_f32 v[100:101], v[100:101], v[20:21]
	v_pk_mul_f32 v[84:85], v[84:85], v[20:21]
	v_pk_mul_f32 v[68:69], v[68:69], v[20:21]
	v_pk_mul_f32 v[52:53], v[52:53], v[20:21]
	v_cvt_pk_bf16_f32 v100, v100, v101
	v_cvt_pk_bf16_f32 v84, v84, v85
	v_cvt_pk_bf16_f32 v68, v68, v69
	v_cvt_pk_bf16_f32 v52, v52, v53
	ds_write_b32 v2, v100 offset:24576
	ds_write_b32 v2, v84 offset:24704
	ds_write_b32 v2, v68 offset:24832
	ds_write_b32 v2, v52 offset:24960
	v_pk_mul_f32 v[102:103], v[102:103], v[22:23]
	v_pk_mul_f32 v[86:87], v[86:87], v[22:23]
	v_pk_mul_f32 v[70:71], v[70:71], v[22:23]
	v_pk_mul_f32 v[54:55], v[54:55], v[22:23]
	v_cvt_pk_bf16_f32 v102, v102, v103
	v_cvt_pk_bf16_f32 v86, v86, v87
	v_cvt_pk_bf16_f32 v70, v70, v71
	v_cvt_pk_bf16_f32 v54, v54, v55
	ds_write_b32 v2, v102 offset:25088
	ds_write_b32 v2, v86 offset:25216
	ds_write_b32 v2, v70 offset:25344
	ds_write_b32 v2, v54 offset:25472
	v_pk_mul_f32 v[104:105], v[104:105], v[24:25]
	v_pk_mul_f32 v[88:89], v[88:89], v[24:25]
	v_pk_mul_f32 v[72:73], v[72:73], v[24:25]
	v_pk_mul_f32 v[56:57], v[56:57], v[24:25]
	v_cvt_pk_bf16_f32 v104, v104, v105
	v_cvt_pk_bf16_f32 v88, v88, v89
	v_cvt_pk_bf16_f32 v72, v72, v73
	v_cvt_pk_bf16_f32 v56, v56, v57
	ds_write_b32 v3, v104
	ds_write_b32 v3, v88 offset:128
	ds_write_b32 v3, v72 offset:256
	ds_write_b32 v3, v56 offset:384
	v_pk_mul_f32 v[106:107], v[106:107], v[26:27]
	v_pk_mul_f32 v[90:91], v[90:91], v[26:27]
	v_pk_mul_f32 v[74:75], v[74:75], v[26:27]
	v_pk_mul_f32 v[58:59], v[58:59], v[26:27]
	v_cvt_pk_bf16_f32 v106, v106, v107
	v_cvt_pk_bf16_f32 v90, v90, v91
	v_cvt_pk_bf16_f32 v74, v74, v75
	v_cvt_pk_bf16_f32 v58, v58, v59
	ds_write_b32 v3, v106 offset:512
	ds_write_b32 v3, v90 offset:640
	ds_write_b32 v3, v74 offset:768
	ds_write_b32 v3, v58 offset:896
	v_pk_mul_f32 v[108:109], v[108:109], v[28:29]
	v_pk_mul_f32 v[92:93], v[92:93], v[28:29]
	v_pk_mul_f32 v[76:77], v[76:77], v[28:29]
	v_pk_mul_f32 v[60:61], v[60:61], v[28:29]
	v_cvt_pk_bf16_f32 v108, v108, v109
	v_cvt_pk_bf16_f32 v92, v92, v93
	v_cvt_pk_bf16_f32 v76, v76, v77
	v_cvt_pk_bf16_f32 v60, v60, v61
	ds_write_b32 v3, v108 offset:24576
	ds_write_b32 v3, v92 offset:24704
	ds_write_b32 v3, v76 offset:24832
	ds_write_b32 v3, v60 offset:24960
	v_pk_mul_f32 v[110:111], v[110:111], v[30:31]
	v_pk_mul_f32 v[94:95], v[94:95], v[30:31]
	v_pk_mul_f32 v[78:79], v[78:79], v[30:31]
	v_pk_mul_f32 v[62:63], v[62:63], v[30:31]
	v_cvt_pk_bf16_f32 v110, v110, v111
	v_cvt_pk_bf16_f32 v94, v94, v95
	v_cvt_pk_bf16_f32 v78, v78, v79
	v_cvt_pk_bf16_f32 v62, v62, v63
	ds_write_b32 v3, v110 offset:25088
	ds_write_b32 v3, v94 offset:25216
	ds_write_b32 v3, v78 offset:25344
	ds_write_b32 v3, v62 offset:25472
	s_waitcnt lgkmcnt(0)
	ds_read_b128 v[112:115], v6
	ds_read_b128 v[116:119], v6 offset:16
	ds_read_b128 v[120:123], v6 offset:24576
	ds_read_b128 v[124:127], v6 offset:24592
	ds_read_b128 v[128:131], v8
	ds_read_b128 v[132:135], v8 offset:16
	ds_read_b128 v[136:139], v8 offset:24576
	ds_read_b128 v[140:143], v8 offset:24592
	s_waitcnt lgkmcnt(6)
	v_perm_b32 v16, v113, v112, s99
	v_perm_b32 v17, v115, v114, s99
	v_perm_b32 v18, v117, v116, s99
	v_perm_b32 v19, v119, v118, s99
	v_perm_b32 v20, v113, v112, s100
	v_perm_b32 v21, v115, v114, s100
	v_perm_b32 v22, v117, v116, s100
	v_perm_b32 v23, v119, v118, s100
	global_store_dwordx4 v7, v[16:19], s[16:17]
	v_add_u32_e32 v10, 0x1000, v7
	global_store_dwordx4 v10, v[20:23], s[16:17]
	s_waitcnt lgkmcnt(4)
	v_perm_b32 v24, v121, v120, s99
	v_perm_b32 v25, v123, v122, s99
	v_perm_b32 v26, v125, v124, s99
	v_perm_b32 v27, v127, v126, s99
	v_perm_b32 v28, v121, v120, s100
	v_perm_b32 v29, v123, v122, s100
	v_perm_b32 v30, v125, v124, s100
	v_perm_b32 v31, v127, v126, s100
	v_add_u32_e32 v9, 0x8000, v7
	global_store_dwordx4 v9, v[24:27], s[16:17]
	v_add_u32_e32 v10, 0x9000, v7
	global_store_dwordx4 v10, v[28:31], s[16:17]
	s_waitcnt lgkmcnt(2)
	v_perm_b32 v32, v129, v128, s99
	v_perm_b32 v33, v131, v130, s99
	v_perm_b32 v34, v133, v132, s99
	v_perm_b32 v35, v135, v134, s99
	v_perm_b32 v36, v129, v128, s100
	v_perm_b32 v37, v131, v130, s100
	v_perm_b32 v38, v133, v132, s100
	v_perm_b32 v39, v135, v134, s100
	v_add_u32_e32 v9, 0x10000, v7
	global_store_dwordx4 v9, v[32:35], s[16:17]
	v_add_u32_e32 v10, 0x11000, v7
	global_store_dwordx4 v10, v[36:39], s[16:17]
	s_waitcnt lgkmcnt(0)
	v_perm_b32 v40, v137, v136, s99
	v_perm_b32 v41, v139, v138, s99
	v_perm_b32 v42, v141, v140, s99
	v_perm_b32 v43, v143, v142, s99
	v_perm_b32 v44, v137, v136, s100
	v_perm_b32 v45, v139, v138, s100
	v_perm_b32 v46, v141, v140, s100
	v_perm_b32 v47, v143, v142, s100
	v_add_u32_e32 v9, 0x18000, v7
	global_store_dwordx4 v9, v[40:43], s[16:17]
	v_add_u32_e32 v10, 0x19000, v7
	global_store_dwordx4 v10, v[44:47], s[16:17]
	s_branch .LBB0_712

.LBB0_1507:
	s_or_b64 exec, exec, s[38:39]
	s_lshr_b32 s78, s84, 6
	s_add_i32 s79, s78, 4
	s_add_u32 s38, s76, s84
	s_addc_u32 s39, s77, 0
	s_lshl_b64 s[20:21], s[38:39], 11
	s_lshl_b64 s[38:39], s[38:39], 12
	v_mov_b32_e32 v2, v176
	s_add_u32 s38, s65, s38
	s_addc_u32 s39, s66, s39
	v_ashrrev_i32_e32 v3, 31, v2
	v_lshl_add_u64 v[2:3], v[2:3], 1, s[38:39]
	v_mov_b32_e32 v14, v0
	v_mov_b32_e32 v15, v0
	s_waitcnt vmcnt(0)
	v_add_u32_e32 v201, s84, v198
	v_mov_b32_e32 v1, v0
	v_mov_b32_e32 v2, v0
	v_mov_b32_e32 v3, v0
	v_mov_b32_e32 v4, v0
	v_mov_b32_e32 v5, v0
	v_mov_b32_e32 v6, v0
	v_mov_b32_e32 v7, v0
	v_mov_b32_e32 v8, v0
	v_mov_b32_e32 v9, v0
	v_mov_b32_e32 v10, v0
	v_mov_b32_e32 v11, v0
	v_mov_b32_e32 v12, v0
	v_mov_b32_e32 v13, v0
	s_add_i32 s84, s84, s52
	v_mov_b64_e32 v[62:63], v[14:15]
	v_mov_b64_e32 v[78:79], v[14:15]
	v_mov_b64_e32 v[94:95], v[14:15]
	v_mov_b64_e32 v[110:111], v[14:15]
	s_mov_b32 s80, 0
	v_mov_b32_e32 v204, 0
	v_mov_b32_e32 v202, 0xf149f2ca
	s_mov_b32 s82, 2
	s_mov_b32 s81, -4
	s_mov_b32 s83, 63
	v_mov_b32_e32 v203, v199
	s_or_b32 s85, s78, 3
	s_or_b32 s86, s84, 31
	v_mov_b64_e32 v[60:61], v[12:13]
	v_mov_b64_e32 v[58:59], v[10:11]
	v_mov_b64_e32 v[56:57], v[8:9]
	v_mov_b64_e32 v[54:55], v[6:7]
	v_mov_b64_e32 v[52:53], v[4:5]
	v_mov_b64_e32 v[50:51], v[2:3]
	v_mov_b64_e32 v[48:49], v[0:1]
	v_mov_b64_e32 v[76:77], v[12:13]
	v_mov_b64_e32 v[74:75], v[10:11]
	v_mov_b64_e32 v[72:73], v[8:9]
	v_mov_b64_e32 v[70:71], v[6:7]
	v_mov_b64_e32 v[68:69], v[4:5]
	v_mov_b64_e32 v[66:67], v[2:3]
	v_mov_b64_e32 v[64:65], v[0:1]
	v_mov_b64_e32 v[92:93], v[12:13]
	v_mov_b64_e32 v[90:91], v[10:11]
	v_mov_b64_e32 v[88:89], v[8:9]
	v_mov_b64_e32 v[86:87], v[6:7]
	v_mov_b64_e32 v[84:85], v[4:5]
	v_mov_b64_e32 v[82:83], v[2:3]
	v_mov_b64_e32 v[80:81], v[0:1]
	v_mov_b64_e32 v[108:109], v[12:13]
	v_mov_b64_e32 v[106:107], v[10:11]
	v_mov_b64_e32 v[104:105], v[8:9]
	v_mov_b64_e32 v[102:103], v[6:7]
	v_mov_b64_e32 v[100:101], v[4:5]
	v_mov_b64_e32 v[98:99], v[2:3]
	v_mov_b64_e32 v[96:97], v[0:1]
	s_waitcnt vmcnt(7)
	s_waitcnt vmcnt(6)
	s_waitcnt vmcnt(5)
	s_waitcnt vmcnt(4)
	s_waitcnt vmcnt(3)
	s_waitcnt vmcnt(2)
	s_waitcnt vmcnt(1)
	s_waitcnt vmcnt(0)
	s_waitcnt lgkmcnt(0)
	s_barrier
	s_cmp_lt_u32 s33, 4
	s_cbranch_scc1 .LPP1_pre
	s_barrier

.LBB0_1509:
	v_add_f32_e32 v14, v14, v15
	v_fmac_f32_e32 v14, v204, v1
	s_cmp_lt_u32 s33, 4
	s_cbranch_scc0 .LPP1_b2
	s_waitcnt vmcnt(4)
.LPP1_b2:
	s_waitcnt lgkmcnt(0)
	s_barrier
	s_setprio 1
	v_lshl_add_u32 v1, s80, 15, v197
	ds_read_b64_tr_b16 v[204:205], v1 offset:0
	ds_read_b64_tr_b16 v[206:207], v1 offset:0x800
	ds_read_b64_tr_b16 v[208:209], v1 offset:0x200
	ds_read_b64_tr_b16 v[210:211], v1 offset:0xa00
	ds_read_b64_tr_b16 v[212:213], v1 offset:0x400
	ds_read_b64_tr_b16 v[214:215], v1 offset:0xc00
	ds_read_b64_tr_b16 v[216:217], v1 offset:0x600
	ds_read_b64_tr_b16 v[218:219], v1 offset:0xe00
	ds_read_b64_tr_b16 v[220:221], v1 offset:0x1000
	ds_read_b64_tr_b16 v[222:223], v1 offset:0x1800
	ds_read_b64_tr_b16 v[224:225], v1 offset:0x1200
	ds_read_b64_tr_b16 v[226:227], v1 offset:0x1a00
	ds_read_b64_tr_b16 v[228:229], v1 offset:0x1400
	ds_read_b64_tr_b16 v[230:231], v1 offset:0x1c00
	ds_read_b64_tr_b16 v[232:233], v1 offset:0x1600
	ds_read_b64_tr_b16 v[234:235], v1 offset:0x1e00
	s_waitcnt lgkmcnt(8)
	s_nop 0
	v_mfma_f32_32x32x16_bf16 v[96:111], v[144:147], v[204:207], v[96:111]
	v_mfma_f32_32x32x16_bf16 v[80:95], v[144:147], v[208:211], v[80:95]
	v_mfma_f32_32x32x16_bf16 v[64:79], v[144:147], v[212:215], v[64:79]
	v_mfma_f32_32x32x16_bf16 v[48:63], v[144:147], v[216:219], v[48:63]
	ds_read_b64_tr_b16 v[144:145], v1 offset:0x2000
	ds_read_b64_tr_b16 v[146:147], v1 offset:0x2800
	ds_read_b64_tr_b16 v[204:205], v1 offset:0x2200
	ds_read_b64_tr_b16 v[206:207], v1 offset:0x2a00
	ds_read_b64_tr_b16 v[208:209], v1 offset:0x2400
	ds_read_b64_tr_b16 v[210:211], v1 offset:0x2c00
	ds_read_b64_tr_b16 v[212:213], v1 offset:0x2600
	ds_read_b64_tr_b16 v[214:215], v1 offset:0x2e00
	s_waitcnt lgkmcnt(8)
	v_mfma_f32_32x32x16_bf16 v[96:111], v[10:13], v[220:223], v[96:111]
	v_mfma_f32_32x32x16_bf16 v[80:95], v[10:13], v[224:227], v[80:95]
	v_mfma_f32_32x32x16_bf16 v[64:79], v[10:13], v[228:231], v[64:79]
	v_mfma_f32_32x32x16_bf16 v[48:63], v[10:13], v[232:235], v[48:63]
	ds_read_b64_tr_b16 v[10:11], v1 offset:0x3000
	ds_read_b64_tr_b16 v[12:13], v1 offset:0x3800
	ds_read_b64_tr_b16 v[216:217], v1 offset:0x3200
	ds_read_b64_tr_b16 v[218:219], v1 offset:0x3a00
	ds_read_b64_tr_b16 v[220:221], v1 offset:0x3400
	ds_read_b64_tr_b16 v[222:223], v1 offset:0x3c00
	ds_read_b64_tr_b16 v[224:225], v1 offset:0x3600
	ds_read_b64_tr_b16 v[226:227], v1 offset:0x3e00
	s_waitcnt lgkmcnt(8)
	v_mfma_f32_32x32x16_bf16 v[96:111], v[6:9], v[144:147], v[96:111]
	v_mfma_f32_32x32x16_bf16 v[80:95], v[6:9], v[204:207], v[80:95]
	v_mfma_f32_32x32x16_bf16 v[64:79], v[6:9], v[208:211], v[64:79]
	v_mfma_f32_32x32x16_bf16 v[48:63], v[6:9], v[212:215], v[48:63]
	s_waitcnt lgkmcnt(0)
	v_mfma_f32_32x32x16_bf16 v[96:111], v[2:5], v[10:13], v[96:111]
	v_mfma_f32_32x32x16_bf16 v[80:95], v[2:5], v[216:219], v[80:95]
	v_mfma_f32_32x32x16_bf16 v[64:79], v[2:5], v[220:223], v[64:79]
	v_mfma_f32_32x32x16_bf16 v[48:63], v[2:5], v[224:227], v[48:63]
	v_mov_b32_e32 v204, v14
.LBB0_1510:
	s_add_i32 s26, s80, 1
	s_cmp_lg_u32 s80, 2
	s_cselect_b32 s80, s26, 0
	s_add_i32 s26, s82, 1
	s_cmp_lg_u32 s82, 2
	s_cselect_b32 s82, s26, 0
	s_add_i32 s81, s81, 1
	s_add_i32 s83, s83, 64
	v_subrev_u32_e32 v201, 64, v201
	s_cmp_eq_u32 s78, s81
	v_add_u32_e32 v203, 0x100, v203
	s_cbranch_scc1 .LBB0_1519

.LPP1_b1:
	s_waitcnt lgkmcnt(0)
	s_barrier
	s_add_i32 s26, s81, 6
	s_cmp_lt_u32 s26, s79
	s_cselect_b32 s26, s26, s85
	s_lshl_b32 s26, s26, 6
	s_lshl_b32 s87, s82, 15
	s_add_i32 s87, s50, s87
	s_lshl_b64 s[88:89], s[26:27], 12
	s_add_u32 s90, s30, s88
	s_addc_u32 s91, s31, s89
	v_lshl_add_u64 v[2:3], s[90:91], 0, v[154:155]
	s_mov_b32 m0, s87
	s_nop 0
	global_load_lds_dwordx4 v[2:3], off
	v_lshl_add_u64 v[2:3], s[90:91], 0, v[152:153]
	s_add_i32 m0, s87, 0x400
	s_nop 0
	global_load_lds_dwordx4 v[2:3], off
	s_add_i32 s26, s81, 5
	s_cmp_lt_u32 s26, s79
	s_cselect_b32 s26, s26, s85
	s_lshl_b32 s26, s26, 6
	s_lshl_b64 s[88:89], s[26:27], 12
	s_add_u32 s88, s34, s88
	s_addc_u32 s89, s35, s89
	s_add_i32 s87, s80, 1
	s_cmp_lg_u32 s80, 2
	s_cselect_b32 s87, s87, 0
	s_lshl_b32 s87, s87, 15
	s_add_i32 s87, s50, s87
	v_lshl_add_u64 v[2:3], s[88:89], 0, v[150:151]
	s_add_i32 m0, s87, 0x4000
	s_nop 0
	global_load_lds_dwordx4 v[2:3], off
	v_lshl_add_u64 v[2:3], s[88:89], 0, v[148:149]
	s_add_i32 m0, s87, 0x4400
	s_nop 0
	global_load_lds_dwordx4 v[2:3], off
	s_cmp_le_u32 s83, s84
	s_cbranch_scc1 .LBB0_1516
	v_cmp_gt_u32_e32 vcc, 2.0, v201
	v_add_u32_e32 v1, 0xbfffffe0, v201
	s_nop 0
	v_cndmask_b32_e32 v16, v200, v16, vcc
	v_cmp_lt_u32_e32 vcc, s61, v1
	v_add_u32_e32 v1, 0xbfffffff, v201
	s_nop 0
	v_cndmask_b32_e32 v32, v200, v32, vcc
	v_cmp_lt_u32_e32 vcc, s61, v1
	v_add_u32_e32 v1, 0xbfffffdf, v201
	s_nop 0
	v_cndmask_b32_e32 v17, v200, v17, vcc
	v_cmp_lt_u32_e32 vcc, s61, v1
	v_add_u32_e32 v1, 0xbffffffe, v201
	s_nop 0
	v_cndmask_b32_e32 v33, v200, v33, vcc
	v_cmp_lt_u32_e32 vcc, s61, v1
	v_add_u32_e32 v1, 0xbfffffde, v201
	s_nop 0
	v_cndmask_b32_e32 v18, v200, v18, vcc
	v_cmp_lt_u32_e32 vcc, s61, v1
	v_add_u32_e32 v1, 0xbffffffd, v201
	s_nop 0
	v_cndmask_b32_e32 v34, v200, v34, vcc
	v_cmp_lt_u32_e32 vcc, s61, v1
	v_add_u32_e32 v1, 0xbfffffdd, v201
	s_nop 0
	v_cndmask_b32_e32 v19, v200, v19, vcc
	v_cmp_lt_u32_e32 vcc, s61, v1
	v_add_u32_e32 v1, 0xbffffff8, v201
	s_nop 0
	v_cndmask_b32_e32 v35, v200, v35, vcc
	v_cmp_lt_u32_e32 vcc, s61, v1
	v_add_u32_e32 v1, 0xbfffffd8, v201
	s_nop 0
	v_cndmask_b32_e32 v20, v200, v20, vcc
	v_cmp_lt_u32_e32 vcc, s61, v1
	v_add_u32_e32 v1, 0xbffffff7, v201
	s_nop 0
	v_cndmask_b32_e32 v36, v200, v36, vcc
	v_cmp_lt_u32_e32 vcc, s61, v1
	v_add_u32_e32 v1, 0xbfffffd7, v201
	s_nop 0
	v_cndmask_b32_e32 v21, v200, v21, vcc
	v_cmp_lt_u32_e32 vcc, s61, v1
	v_add_u32_e32 v1, 0xbffffff6, v201
	s_nop 0
	v_cndmask_b32_e32 v37, v200, v37, vcc
	v_cmp_lt_u32_e32 vcc, s61, v1
	v_add_u32_e32 v1, 0xbfffffd6, v201
	s_nop 0
	v_cndmask_b32_e32 v22, v200, v22, vcc
	v_cmp_lt_u32_e32 vcc, s61, v1
	v_add_u32_e32 v1, 0xbffffff5, v201
	s_nop 0
	v_cndmask_b32_e32 v38, v200, v38, vcc
	v_cmp_lt_u32_e32 vcc, s61, v1
	v_add_u32_e32 v1, 0xbfffffd5, v201
	s_nop 0
	v_cndmask_b32_e32 v23, v200, v23, vcc
	v_cmp_lt_u32_e32 vcc, s61, v1
	v_add_u32_e32 v1, 0xbffffff0, v201
	s_nop 0
	v_cndmask_b32_e32 v39, v200, v39, vcc
	v_cmp_lt_u32_e32 vcc, s61, v1
	v_add_u32_e32 v1, 0xbfffffd0, v201
	s_nop 0
	v_cndmask_b32_e32 v24, v200, v24, vcc
	v_cmp_lt_u32_e32 vcc, s61, v1
	v_add_u32_e32 v1, 0xbfffffef, v201
	s_nop 0
	v_cndmask_b32_e32 v40, v200, v40, vcc
	v_cmp_lt_u32_e32 vcc, s61, v1
	v_add_u32_e32 v1, 0xbfffffcf, v201
	s_nop 0
	v_cndmask_b32_e32 v25, v200, v25, vcc
	v_cmp_lt_u32_e32 vcc, s61, v1
	v_add_u32_e32 v1, 0xbfffffee, v201
	s_nop 0
	v_cndmask_b32_e32 v41, v200, v41, vcc
	v_cmp_lt_u32_e32 vcc, s61, v1
	v_add_u32_e32 v1, 0xbfffffce, v201
	s_nop 0
	v_cndmask_b32_e32 v26, v200, v26, vcc
	v_cmp_lt_u32_e32 vcc, s61, v1
	v_add_u32_e32 v1, 0xbfffffed, v201
	s_nop 0
	v_cndmask_b32_e32 v42, v200, v42, vcc
	v_cmp_lt_u32_e32 vcc, s61, v1
	v_add_u32_e32 v1, 0xbfffffcd, v201
	s_nop 0
	v_cndmask_b32_e32 v27, v200, v27, vcc
	v_cmp_lt_u32_e32 vcc, s61, v1
	v_add_u32_e32 v1, 0xbfffffe8, v201
	s_nop 0
	v_cndmask_b32_e32 v43, v200, v43, vcc
	v_cmp_lt_u32_e32 vcc, s61, v1
	v_add_u32_e32 v1, 0xbfffffc8, v201
	s_nop 0
	v_cndmask_b32_e32 v28, v200, v28, vcc
	v_cmp_lt_u32_e32 vcc, s61, v1
	v_add_u32_e32 v1, 0xbfffffe7, v201
	s_nop 0
	v_cndmask_b32_e32 v44, v200, v44, vcc
	v_cmp_lt_u32_e32 vcc, s61, v1
	v_add_u32_e32 v1, 0xbfffffc7, v201
	s_nop 0
	v_cndmask_b32_e32 v29, v200, v29, vcc
	v_cmp_lt_u32_e32 vcc, s61, v1
	v_add_u32_e32 v1, 0xbfffffe6, v201
	s_nop 0
	v_cndmask_b32_e32 v45, v200, v45, vcc
	v_cmp_lt_u32_e32 vcc, s61, v1
	v_add_u32_e32 v1, 0xbfffffc6, v201
	s_nop 0
	v_cndmask_b32_e32 v30, v200, v30, vcc
	v_cmp_lt_u32_e32 vcc, s61, v1
	v_add_u32_e32 v1, 0xbfffffe5, v201
	s_nop 0
	v_cndmask_b32_e32 v46, v200, v46, vcc
	v_cmp_lt_u32_e32 vcc, s61, v1
	v_add_u32_e32 v1, 0xbfffffc5, v201
	s_nop 0
	v_cndmask_b32_e32 v31, v200, v31, vcc
	v_cmp_lt_u32_e32 vcc, s61, v1
	s_nop 1
	v_cndmask_b32_e32 v47, v200, v47, vcc

.LPP1_noact:
	s_cmp_lt_u32 s33, 4
	s_cbranch_scc1 .LPP1_na1
	s_waitcnt vmcnt(0)
	s_barrier
	s_add_i32 s26, s81, 6
	s_cmp_lt_u32 s26, s79
	s_cselect_b32 s26, s26, s85
	s_lshl_b32 s26, s26, 6
	s_lshl_b32 s87, s82, 15
	s_add_i32 s87, s50, s87
	s_lshl_b64 s[88:89], s[26:27], 12
	s_add_u32 s90, s30, s88
	s_addc_u32 s91, s31, s89
	v_lshl_add_u64 v[2:3], s[90:91], 0, v[154:155]
	s_mov_b32 m0, s87
	s_nop 0
	global_load_lds_dwordx4 v[2:3], off
	v_lshl_add_u64 v[2:3], s[90:91], 0, v[152:153]
	s_add_i32 m0, s87, 0x400
	s_nop 0
	global_load_lds_dwordx4 v[2:3], off
	s_add_i32 s26, s81, 5
	s_cmp_lt_u32 s26, s79
	s_cselect_b32 s26, s26, s85
	s_lshl_b32 s26, s26, 6
	s_lshl_b64 s[88:89], s[26:27], 12
	s_add_u32 s88, s34, s88
	s_addc_u32 s89, s35, s89
	s_add_i32 s87, s80, 1
	s_cmp_lg_u32 s80, 2
	s_cselect_b32 s87, s87, 0
	s_lshl_b32 s87, s87, 15
	s_add_i32 s87, s50, s87
	v_lshl_add_u64 v[2:3], s[88:89], 0, v[150:151]
	s_add_i32 m0, s87, 0x4000
	s_nop 0
	global_load_lds_dwordx4 v[2:3], off
	v_lshl_add_u64 v[2:3], s[88:89], 0, v[148:149]
	s_add_i32 m0, s87, 0x4400
	s_nop 0
	global_load_lds_dwordx4 v[2:3], off
	s_barrier
	s_branch .LBB0_1510
.LPP1_na1:
	s_barrier
	s_add_i32 s26, s81, 6
	s_cmp_lt_u32 s26, s79
	s_cselect_b32 s26, s26, s85
	s_lshl_b32 s26, s26, 6
	s_lshl_b32 s87, s82, 15
	s_add_i32 s87, s50, s87
	s_lshl_b64 s[88:89], s[26:27], 12
	s_add_u32 s90, s30, s88
	s_addc_u32 s91, s31, s89
	v_lshl_add_u64 v[2:3], s[90:91], 0, v[154:155]
	s_mov_b32 m0, s87
	s_nop 0
	global_load_lds_dwordx4 v[2:3], off
	v_lshl_add_u64 v[2:3], s[90:91], 0, v[152:153]
	s_add_i32 m0, s87, 0x400
	s_nop 0
	global_load_lds_dwordx4 v[2:3], off
	s_add_i32 s26, s81, 5
	s_cmp_lt_u32 s26, s79
	s_cselect_b32 s26, s26, s85
	s_lshl_b32 s26, s26, 6
	s_lshl_b64 s[88:89], s[26:27], 12
	s_add_u32 s88, s34, s88
	s_addc_u32 s89, s35, s89
	s_add_i32 s87, s80, 1
	s_cmp_lg_u32 s80, 2
	s_cselect_b32 s87, s87, 0
	s_lshl_b32 s87, s87, 15
	s_add_i32 s87, s50, s87
	v_lshl_add_u64 v[2:3], s[88:89], 0, v[150:151]
	s_add_i32 m0, s87, 0x4000
	s_nop 0
	global_load_lds_dwordx4 v[2:3], off
	v_lshl_add_u64 v[2:3], s[88:89], 0, v[148:149]
	s_add_i32 m0, s87, 0x4400
	s_nop 0
	global_load_lds_dwordx4 v[2:3], off
	s_waitcnt vmcnt(4)
	s_barrier
	s_branch .LBB0_1510

.LPP1_fin:
	s_barrier
	s_waitcnt vmcnt(0)
	s_and_saveexec_b64 s[38:39], s[4:5]
	ds_write_b32 v187, v204
	s_or_b64 exec, exec, s[38:39]
	v_mbcnt_lo_u32_b32 v1, -1, 0
	v_mbcnt_hi_u32_b32 v1, -1, v1
	s_lshl_b32 s98, s33, 11
	s_mov_b32 s99, 0x5040100
	s_mov_b32 s100, 0x7060302
	s_waitcnt lgkmcnt(0)
	ds_read_b128 v[32:35], v189
	ds_read_b128 v[36:39], v189 offset:32
	ds_read_b128 v[40:43], v189 offset:64
	ds_read_b128 v[44:47], v189 offset:96
	s_lshl_b64 s[20:21], s[20:21], 1
	s_add_u32 s20, s67, s20
	s_addc_u32 s21, s75, s21
	v_lshrrev_b32_e32 v2, 5, v1
	v_and_b32_e32 v3, 31, v1
	v_lshlrev_b32_e32 v2, 10, v2
	v_lshl_add_u32 v2, v3, 2, v2
	v_add_u32_e32 v2, s98, v2
	v_lshrrev_b32_e32 v4, 4, v1
	v_and_b32_e32 v5, 15, v1
	v_lshlrev_b32_e32 v6, 9, v4
	v_lshl_add_u32 v6, v5, 5, v6
	v_add_u32_e32 v6, s98, v6
	v_lshlrev_b32_e32 v7, 13, v4
	v_lshl_add_u32 v7, v5, 4, v7
	s_waitcnt lgkmcnt(0)
	v_rcp_f32_e32 v16, v32
	v_rcp_f32_e32 v17, v33
	v_rcp_f32_e32 v18, v34
	v_rcp_f32_e32 v19, v35
	v_rcp_f32_e32 v20, v36
	v_rcp_f32_e32 v21, v37
	v_rcp_f32_e32 v22, v38
	v_rcp_f32_e32 v23, v39
	v_rcp_f32_e32 v24, v40
	v_rcp_f32_e32 v25, v41
	v_rcp_f32_e32 v26, v42
	v_rcp_f32_e32 v27, v43
	v_rcp_f32_e32 v28, v44
	v_rcp_f32_e32 v29, v45
	v_rcp_f32_e32 v30, v46
	v_rcp_f32_e32 v31, v47
	s_nop 0
	v_pk_mul_f32 v[96:97], v[96:97], v[16:17]
	v_pk_mul_f32 v[80:81], v[80:81], v[16:17]
	v_pk_mul_f32 v[64:65], v[64:65], v[16:17]
	v_pk_mul_f32 v[48:49], v[48:49], v[16:17]
	v_cvt_pk_bf16_f32 v96, v96, v97
	v_cvt_pk_bf16_f32 v80, v80, v81
	v_cvt_pk_bf16_f32 v64, v64, v65
	v_cvt_pk_bf16_f32 v48, v48, v49
	ds_write_b32 v2, v96
	ds_write_b32 v2, v80 offset:128
	ds_write_b32 v2, v64 offset:256
	ds_write_b32 v2, v48 offset:384
	v_pk_mul_f32 v[98:99], v[98:99], v[18:19]
	v_pk_mul_f32 v[82:83], v[82:83], v[18:19]
	v_pk_mul_f32 v[66:67], v[66:67], v[18:19]
	v_pk_mul_f32 v[50:51], v[50:51], v[18:19]
	v_cvt_pk_bf16_f32 v98, v98, v99
	v_cvt_pk_bf16_f32 v82, v82, v83
	v_cvt_pk_bf16_f32 v66, v66, v67
	v_cvt_pk_bf16_f32 v50, v50, v51
	ds_write_b32 v2, v98 offset:512
	ds_write_b32 v2, v82 offset:640
	ds_write_b32 v2, v66 offset:768
	ds_write_b32 v2, v50 offset:896
	v_pk_mul_f32 v[100:101], v[100:101], v[20:21]
	v_pk_mul_f32 v[84:85], v[84:85], v[20:21]
	v_pk_mul_f32 v[68:69], v[68:69], v[20:21]
	v_pk_mul_f32 v[52:53], v[52:53], v[20:21]
	v_cvt_pk_bf16_f32 v100, v100, v101
	v_cvt_pk_bf16_f32 v84, v84, v85
	v_cvt_pk_bf16_f32 v68, v68, v69
	v_cvt_pk_bf16_f32 v52, v52, v53
	ds_write_b32 v2, v100 offset:16384
	ds_write_b32 v2, v84 offset:16512
	ds_write_b32 v2, v68 offset:16640
	ds_write_b32 v2, v52 offset:16768
	v_pk_mul_f32 v[102:103], v[102:103], v[22:23]
	v_pk_mul_f32 v[86:87], v[86:87], v[22:23]
	v_pk_mul_f32 v[70:71], v[70:71], v[22:23]
	v_pk_mul_f32 v[54:55], v[54:55], v[22:23]
	v_cvt_pk_bf16_f32 v102, v102, v103
	v_cvt_pk_bf16_f32 v86, v86, v87
	v_cvt_pk_bf16_f32 v70, v70, v71
	v_cvt_pk_bf16_f32 v54, v54, v55
	ds_write_b32 v2, v102 offset:16896
	ds_write_b32 v2, v86 offset:17024
	ds_write_b32 v2, v70 offset:17152
	ds_write_b32 v2, v54 offset:17280
	v_pk_mul_f32 v[104:105], v[104:105], v[24:25]
	v_pk_mul_f32 v[88:89], v[88:89], v[24:25]
	v_pk_mul_f32 v[72:73], v[72:73], v[24:25]
	v_pk_mul_f32 v[56:57], v[56:57], v[24:25]
	v_cvt_pk_bf16_f32 v104, v104, v105
	v_cvt_pk_bf16_f32 v88, v88, v89
	v_cvt_pk_bf16_f32 v72, v72, v73
	v_cvt_pk_bf16_f32 v56, v56, v57
	ds_write_b32 v2, v104 offset:32768
	ds_write_b32 v2, v88 offset:32896
	ds_write_b32 v2, v72 offset:33024
	ds_write_b32 v2, v56 offset:33152
	v_pk_mul_f32 v[106:107], v[106:107], v[26:27]
	v_pk_mul_f32 v[90:91], v[90:91], v[26:27]
	v_pk_mul_f32 v[74:75], v[74:75], v[26:27]
	v_pk_mul_f32 v[58:59], v[58:59], v[26:27]
	v_cvt_pk_bf16_f32 v106, v106, v107
	v_cvt_pk_bf16_f32 v90, v90, v91
	v_cvt_pk_bf16_f32 v74, v74, v75
	v_cvt_pk_bf16_f32 v58, v58, v59
	ds_write_b32 v2, v106 offset:33280
	ds_write_b32 v2, v90 offset:33408
	ds_write_b32 v2, v74 offset:33536
	ds_write_b32 v2, v58 offset:33664
	v_pk_mul_f32 v[108:109], v[108:109], v[28:29]
	v_pk_mul_f32 v[92:93], v[92:93], v[28:29]
	v_pk_mul_f32 v[76:77], v[76:77], v[28:29]
	v_pk_mul_f32 v[60:61], v[60:61], v[28:29]
	v_cvt_pk_bf16_f32 v108, v108, v109
	v_cvt_pk_bf16_f32 v92, v92, v93
	v_cvt_pk_bf16_f32 v76, v76, v77
	v_cvt_pk_bf16_f32 v60, v60, v61
	ds_write_b32 v2, v108 offset:49152
	ds_write_b32 v2, v92 offset:49280
	ds_write_b32 v2, v76 offset:49408
	ds_write_b32 v2, v60 offset:49536
	v_pk_mul_f32 v[110:111], v[110:111], v[30:31]
	v_pk_mul_f32 v[94:95], v[94:95], v[30:31]
	v_pk_mul_f32 v[78:79], v[78:79], v[30:31]
	v_pk_mul_f32 v[62:63], v[62:63], v[30:31]
	v_cvt_pk_bf16_f32 v110, v110, v111
	v_cvt_pk_bf16_f32 v94, v94, v95
	v_cvt_pk_bf16_f32 v78, v78, v79
	v_cvt_pk_bf16_f32 v62, v62, v63
	ds_write_b32 v2, v110 offset:49664
	ds_write_b32 v2, v94 offset:49792
	ds_write_b32 v2, v78 offset:49920
	ds_write_b32 v2, v62 offset:50048
	s_waitcnt lgkmcnt(0)
	ds_read_b128 v[112:115], v6
	ds_read_b128 v[116:119], v6 offset:16
	ds_read_b128 v[120:123], v6 offset:16384
	ds_read_b128 v[124:127], v6 offset:16400
	ds_read_b128 v[128:131], v6 offset:32768
	ds_read_b128 v[132:135], v6 offset:32784
	ds_read_b128 v[136:139], v6 offset:49152
	ds_read_b128 v[140:143], v6 offset:49168
	s_waitcnt lgkmcnt(6)
	v_perm_b32 v16, v113, v112, s99
	v_perm_b32 v17, v115, v114, s99
	v_perm_b32 v18, v117, v116, s99
	v_perm_b32 v19, v119, v118, s99
	v_perm_b32 v20, v113, v112, s100
	v_perm_b32 v21, v115, v114, s100
	v_perm_b32 v22, v117, v116, s100
	v_perm_b32 v23, v119, v118, s100
	global_store_dwordx4 v7, v[16:19], s[20:21]
	v_add_u32_e32 v10, 0x1000, v7
	global_store_dwordx4 v10, v[20:23], s[20:21]
	s_waitcnt lgkmcnt(4)
	v_perm_b32 v24, v121, v120, s99
	v_perm_b32 v25, v123, v122, s99
	v_perm_b32 v26, v125, v124, s99
	v_perm_b32 v27, v127, v126, s99
	v_perm_b32 v28, v121, v120, s100
	v_perm_b32 v29, v123, v122, s100
	v_perm_b32 v30, v125, v124, s100
	v_perm_b32 v31, v127, v126, s100
	v_add_u32_e32 v9, 0x8000, v7
	global_store_dwordx4 v9, v[24:27], s[20:21]
	v_add_u32_e32 v10, 0x9000, v7
	global_store_dwordx4 v10, v[28:31], s[20:21]
	s_waitcnt lgkmcnt(2)
	v_perm_b32 v32, v129, v128, s99
	v_perm_b32 v33, v131, v130, s99
	v_perm_b32 v34, v133, v132, s99
	v_perm_b32 v35, v135, v134, s99
	v_perm_b32 v36, v129, v128, s100
	v_perm_b32 v37, v131, v130, s100
	v_perm_b32 v38, v133, v132, s100
	v_perm_b32 v39, v135, v134, s100
	v_add_u32_e32 v9, 0x10000, v7
	global_store_dwordx4 v9, v[32:35], s[20:21]
	v_add_u32_e32 v10, 0x11000, v7
	global_store_dwordx4 v10, v[36:39], s[20:21]
	s_waitcnt lgkmcnt(0)
	v_perm_b32 v40, v137, v136, s99
	v_perm_b32 v41, v139, v138, s99
	v_perm_b32 v42, v141, v140, s99
	v_perm_b32 v43, v143, v142, s99
	v_perm_b32 v44, v137, v136, s100
	v_perm_b32 v45, v139, v138, s100
	v_perm_b32 v46, v141, v140, s100
	v_perm_b32 v47, v143, v142, s100
	v_add_u32_e32 v9, 0x18000, v7
	global_store_dwordx4 v9, v[40:43], s[20:21]
	v_add_u32_e32 v10, 0x19000, v7
	global_store_dwordx4 v10, v[44:47], s[20:21]
	s_branch .LBB0_1483
